# hyena loop: running LDS pointers (4 VALU per two lags instead of 20)
# speedup vs baseline: 1.0077x; 1.0025x over previous
; #define LAS __attribute__((address_space(3)))
; DI void hyena_unit(const Inputs& in, int l, unsigned char* ws, int half, int c, LAS unsigned char* lds, int tid) {
;     ...
;     const LAS unsigned char* Zb = Zl + (size_t)b0 * ZSP * 2;
;     const int zstep = ZSP * 2;
;     int s0 = L - 32 * dlo - i32 + 8 * g;
;     const LAS unsigned char* zp0 = Zb + ((32 + a0 + i32 - dlo) * 40 + 8 * g) * 2;
;     ...
;     for (int d = dlo; d <= dhi; ++d) {
; #pragma unroll
;         for (int jh = 0; jh < 2; ++jh) { const bf16x8 a = HY_A(jh);
;             acc0 = __builtin_amdgcn_mfma_f32_32x32x16_bf16(a, HY_B(0, jh), acc0, 0, 0, 0);
;             acc1 = __builtin_amdgcn_mfma_f32_32x32x16_bf16(a, HY_B(1, jh), acc1, 0, 0, 0); }
;         s0 -= 32; zp0 -= 80;
;     }
.LBB0_660:
	v_lshlrev_b32_e32 v46, 1, v32
	v_subrev_u32_e32 v47, 32, v46
	v_and_b32_e32 v47, -4, v47
	v_add_u32_e32 v47, v91, v47
	v_subrev_u32_e32 v47, 64, v47
	v_and_b32_e32 v48, -4, v46
	v_add_u32_e32 v48, v91, v48
	v_subrev_u32_e32 v48, 64, v48
	v_subrev_u32_e32 v33, 0x50, v104
	v_subrev_u32_e32 v50, 0x50, v105
	ds_read_b128 v[142:145], v33 offset:80
	ds_read2_b32 v[134:135], v47 offset0:16 offset1:17
	ds_read2_b32 v[136:137], v47 offset0:18 offset1:19
	ds_read_b128 v[150:153], v50 offset:80
	ds_read_b128 v[146:149], v33 offset:112
	ds_read2_b32 v[138:139], v48 offset0:16 offset1:17
	ds_read2_b32 v[140:141], v48 offset0:18 offset1:19
	ds_read_b128 v[154:157], v50 offset:112
	s_addk_i32 s42, 0xffb0
.Lhy_loop:
	ds_read_b128 v[166:169], v33
	ds_read2_b32 v[158:159], v47 offset0:0 offset1:1
	ds_read2_b32 v[160:161], v47 offset0:2 offset1:3
	ds_read_b128 v[34:37], v50
	ds_read_b128 v[170:173], v33 offset:32
	ds_read2_b32 v[162:163], v48 offset0:0 offset1:1
	ds_read2_b32 v[164:165], v48 offset0:2 offset1:3
	ds_read_b128 v[42:45], v50 offset:32
	s_addk_i32 s42, 0xffb0
	v_subrev_u32_e32 v47, 0x80, v47
	v_subrev_u32_e32 v48, 0x80, v48
	v_subrev_u32_e32 v33, 0xa0, v33
	v_subrev_u32_e32 v50, 0xa0, v50
	s_waitcnt lgkmcnt(8)
	v_mfma_f32_32x32x16_bf16 v[16:31], v[134:137], v[142:145], v[16:31]
	v_mfma_f32_32x32x16_bf16 v[0:15], v[134:137], v[150:153], v[0:15]
	v_mfma_f32_32x32x16_bf16 v[16:31], v[138:141], v[146:149], v[16:31]
	v_mfma_f32_32x32x16_bf16 v[0:15], v[138:141], v[154:157], v[0:15]
	s_add_i32 s74, s81, s42
	s_cmp_lg_u32 s74, 0xffffffb0
	s_cbranch_scc0 .Lhy_done
	ds_read_b128 v[142:145], v33 offset:80
	ds_read2_b32 v[134:135], v47 offset0:16 offset1:17
	ds_read2_b32 v[136:137], v47 offset0:18 offset1:19
	ds_read_b128 v[150:153], v50 offset:80
	ds_read_b128 v[146:149], v33 offset:112
	ds_read2_b32 v[138:139], v48 offset0:16 offset1:17
	ds_read2_b32 v[140:141], v48 offset0:18 offset1:19
	ds_read_b128 v[154:157], v50 offset:112
	s_addk_i32 s42, 0xffb0
	s_waitcnt lgkmcnt(8)
	v_mfma_f32_32x32x16_bf16 v[16:31], v[158:161], v[166:169], v[16:31]
	v_mfma_f32_32x32x16_bf16 v[0:15], v[158:161], v[34:37], v[0:15]
	v_mfma_f32_32x32x16_bf16 v[16:31], v[162:165], v[170:173], v[16:31]
	v_mfma_f32_32x32x16_bf16 v[0:15], v[162:165], v[42:45], v[0:15]
	s_add_i32 s74, s81, s42
	s_cmp_lg_u32 s74, 0xffffffb0
	s_cbranch_scc1 .Lhy_loop
